# attention static s_setprio 1 on waves 0-3 instead of 4-7
# baseline (speedup 1.0000x reference)
; __device__ __forceinline__ void attn_unit(const Params& p, int b, int h, int qb, unsigned char* lds) {
;     const int tid = threadIdx.x, lane = tid & 63, r32 = lane & 31, hi = lane >> 5, wid = __builtin_amdgcn_readfirstlane(tid >> 6);
;     const bf16* qg = (const bf16*)(p.ws + WS_Q); const bf16* kn = (const bf16*)(p.ws + WS_KN); const bf16* kr = (const bf16*)(p.ws + WS_KR); const bf16* vt = (const bf16*)(p.ws + WS_VT);
;     bf16* mix = (bf16*)(p.ws + WS_MIX);
;     const int rowbase = b * SEQ, q0 = qb * 256;
;     const int qrow = rowbase + q0 + wid * 32 + r32, qpos = q0 + wid * 32 + r32;
.LBB0_472:
	v_readfirstlane_b32 s42, v208
	s_nop 3
	s_cmpk_gt_u32 s42, 0xff
	s_cbranch_scc1 .Lattn_prio_done
	s_setprio 1
